# v8 with the stagger delay guarded by the placement census and grid==256 (falls back to no delay), padded to keep code placement
# baseline (speedup 1.0000x reference)
; __device__ __forceinline__ void xcd_barrier(const XcdBarrier& b) {
;     ...
;     }
;     __syncthreads();
; }
.LBB0_765:
	s_or_b64 exec, exec, s[8:9]
	s_cmp_eq_u32 s99, 0
	s_cbranch_scc1 .Lstag_skip
	s_cmpk_lg_u32 s30, 0x100
	s_cbranch_scc1 .Lstag_skip
	s_bfe_u32 s4, s2, 0x10003
	s_cmp_eq_u32 s4, 0
	s_cbranch_scc1 .Lstag_skip
	s_movk_i32 s10, 3

; __device__ __forceinline__ void xcd_barrier(const XcdBarrier& b) {
;     ...
;     __syncthreads();
; }
.Lstag_skip:
	s_nop 0
	s_nop 0
	s_nop 0
	s_nop 0
	s_nop 0
	s_nop 0
	s_nop 0
	s_nop 0
	s_nop 0
	s_nop 0
	s_nop 0
	s_nop 0
	s_lshl_b32 s4, s84, 5
	s_and_b32 s70, s4, 0x60
	s_lshr_b32 s71, s70, 3
	s_cmpk_lt_i32 s2, 0x100
	s_movk_i32 s12, 0x200
	s_movk_i32 s8, 0x200
	s_cselect_b64 s[14:15], -1, 0
	s_cmpk_gt_i32 s2, 0xff
	s_waitcnt lgkmcnt(0)
	s_barrier
	v_mbcnt_lo_u32_b32 v12, -1, 0
	v_mbcnt_hi_u32_b32 v12, -1, v12
	s_cbranch_scc1 .LBB0_794
	s_cmp_gt_i32 s89, -1
	s_cbranch_scc0 .LBB0_768
	s_lshl_b32 s9, s89, 5
	s_cbranch_execz .LBB0_769
	s_branch .LBB0_770
